# NA phase: staging loads of the next item issued during the current item's compute (cross-item software pipeline, mode-dispatched item decode)
# speedup vs baseline: 1.0146x; 1.0124x over previous
.LBB0_501:
	v_mov_b32_e32 v12, v195
	v_readlane_b32 s24, v253, 5
	s_cmpk_gt_i32 s24, 0x9ff
	s_cbranch_scc1 .LBB0_659
	s_waitcnt vmcnt(1)
	v_lshrrev_b32_e32 v0, 1, v12
	v_and_b32_e32 v14, 24, v0
	v_lshlrev_b32_e32 v0, 1, v12
	v_and_b32_e32 v0, 24, v0
	v_and_or_b32 v31, v12, 3, v0
	v_add_u32_e32 v0, 64, v242
	v_cmp_lt_i32_e32 vcc, v237, v0
	s_movk_i32 s0, 0x1d1
	v_and_b32_e32 v17, 15, v12
	v_cndmask_b32_e32 v1, v220, v237, vcc
	v_cmp_lt_i32_e32 vcc, v236, v0
	v_cmp_gt_i32_e64 s[2:3], s0, v12
	v_lshlrev_b32_e32 v16, 1, v14
	v_cndmask_b32_e32 v0, v220, v236, vcc
	v_lshlrev_b32_e32 v77, 2, v0
	v_max_i32_e32 v0, 0xffffffd1, v12
	v_sub_u32_e32 v0, v0, v12
	v_add_u32_e32 v0, 0x1ff, v0
	v_lshlrev_b32_e32 v76, 2, v1
	s_movk_i32 s0, 0x3d0
	v_lshrrev_b32_e32 v1, 9, v0
	v_mad_u32_u24 v78, v17, s0, v16
	v_add_u32_e32 v1, 1, v1
	s_movk_i32 s0, 0x2200
	s_mul_i32 s26, s36, 0x744
	v_cmp_gt_u32_e32 vcc, s0, v0
	v_and_b32_e32 v81, 0xfffffe, v1
	v_lshlrev_b32_e32 v83, 2, v12
	v_ashrrev_i32_e32 v15, 6, v12
	s_lshl_b32 s25, s36, 2
	v_and_b32_e32 v79, 0xfffffe00, v0
	v_add_u32_e32 v80, s26, v12
	v_lshl_add_u32 v82, v81, 9, v12
	v_add_u32_e32 v13, 0x200, v12
	v_cmp_ne_u32_e64 s[4:5], v1, v81
	v_add_u32_e32 v84, 0x1fb00, v83
	v_lshlrev_b32_e32 v85, 3, v12
	s_mov_b32 s27, 0
	s_xor_b64 s[20:21], vcc, -1
	s_mov_b32 s28, s24
	s_mov_b32 s29, s24
	s_mov_b32 s98, 1
	s_mov_b32 s99, 0
	s_branch .LBB0_504
.LBB0_503:
	s_or_b64 exec, exec, s[6:7]
	s_mov_b32 s0, 0xff61b1e6
	v_max3_f32 v0, v26, s0, v24
	v_max3_f32 v0, v0, v28, v25
	v_max3_f32 v0, v0, v34, v23
	v_max3_f32 v0, v0, v29, v27
	v_max3_f32 v0, v0, v32, v30
	v_max3_f32 v0, v0, v36, v35
	v_max3_f32 v0, v0, v38, v37
	v_max3_f32 v0, v0, v40, v39
	v_max3_f32 v0, v0, v42, v41
	v_max3_f32 v0, v0, v48, v43
	v_max3_f32 v0, v0, v51, v50
	v_max3_f32 v0, v0, v55, v54
	v_max3_f32 v0, v0, v61, v60
	v_max3_f32 v0, v0, v63, v62
	v_max3_f32 v0, v0, v88, v87
	v_max3_f32 v0, v0, v90, v89
	v_max3_f32 v0, v0, v92, v91
	v_max3_f32 v0, v0, v94, v93
	v_max3_f32 v0, v0, v96, v95
	v_max3_f32 v0, v0, v98, v97
	v_max3_f32 v0, v0, v100, v99
	v_max3_f32 v0, v0, v102, v101
	v_max3_f32 v0, v0, v104, v103
	v_max3_f32 v0, v0, v106, v105
	v_max3_f32 v0, v0, v108, v107
	v_max3_f32 v0, v0, v110, v109
	v_max3_f32 v0, v0, v112, v111
	v_max3_f32 v0, v0, v114, v113
	v_max3_f32 v0, v0, v116, v115
	v_max3_f32 v0, v0, v8, v9
	v_max3_f32 v0, v0, v22, v117
	v_max3_f32 v0, v0, v119, v118
	ds_bpermute_b32 v1, v76, v0
	s_mov_b32 s0, 0xa000000
	s_mov_b64 s[6:7], 0xa000400
	s_add_i32 s27, s27, 1
	s_waitcnt lgkmcnt(0)
	v_max_f32_e32 v1, v1, v1
	v_max_f32_e32 v0, v0, v1
	ds_bpermute_b32 v1, v77, v0
	s_waitcnt lgkmcnt(0)
	v_max_f32_e32 v1, v1, v1
	v_max_f32_e32 v120, v0, v1
	v_sub_f32_e32 v1, v24, v120
	v_mul_f32_e32 v1, 0x3fb8aa3b, v1
	v_exp_f32_e32 v47, v1
	v_sub_f32_e32 v1, v28, v120
	v_mul_f32_e32 v1, 0x3fb8aa3b, v1
	v_exp_f32_e32 v56, v1
	v_sub_f32_e32 v1, v25, v120
	v_mul_f32_e32 v1, 0x3fb8aa3b, v1
	v_exp_f32_e32 v57, v1
	v_sub_f32_e32 v1, v34, v120
	v_mul_f32_e32 v1, 0x3fb8aa3b, v1
	v_exp_f32_e32 v66, v1
	v_sub_f32_e32 v1, v23, v120
	v_mul_f32_e32 v1, 0x3fb8aa3b, v1
	v_exp_f32_e32 v67, v1
	v_sub_f32_e32 v1, v29, v120
	v_mul_f32_e32 v1, 0x3fb8aa3b, v1
	v_exp_f32_e32 v70, v1
	v_sub_f32_e32 v1, v27, v120
	v_mul_f32_e32 v1, 0x3fb8aa3b, v1
	v_exp_f32_e32 v71, v1
	v_sub_f32_e32 v1, v32, v120
	v_mul_f32_e32 v1, 0x3fb8aa3b, v1
	v_exp_f32_e32 v64, v1
	v_sub_f32_e32 v1, v30, v120
	v_mul_f32_e32 v1, 0x3fb8aa3b, v1
	v_exp_f32_e32 v65, v1
	v_sub_f32_e32 v1, v36, v120
	v_mul_f32_e32 v1, 0x3fb8aa3b, v1
	v_exp_f32_e32 v68, v1
	v_sub_f32_e32 v1, v35, v120
	v_mul_f32_e32 v1, 0x3fb8aa3b, v1
	v_exp_f32_e32 v69, v1
	v_sub_f32_e32 v1, v38, v120
	v_mul_f32_e32 v1, 0x3fb8aa3b, v1
	v_exp_f32_e32 v72, v1
	v_sub_f32_e32 v1, v37, v120
	v_mul_f32_e32 v1, 0x3fb8aa3b, v1
	v_exp_f32_e32 v73, v1
	v_sub_f32_e32 v1, v40, v120
	v_mul_f32_e32 v1, 0x3fb8aa3b, v1
	v_exp_f32_e32 v74, v1
	v_sub_f32_e32 v1, v39, v120
	v_mul_f32_e32 v1, 0x3fb8aa3b, v1
	v_exp_f32_e32 v75, v1
	v_sub_f32_e32 v1, v42, v120
	v_mul_f32_e32 v1, 0x3fb8aa3b, v1
	v_exp_f32_e32 v44, v1
	v_sub_f32_e32 v1, v41, v120
	v_mul_f32_e32 v1, 0x3fb8aa3b, v1
	v_exp_f32_e32 v45, v1
	v_sub_f32_e32 v1, v48, v120
	v_mul_f32_e32 v1, 0x3fb8aa3b, v1
	v_exp_f32_e32 v48, v1
	v_sub_f32_e32 v1, v43, v120
	v_mul_f32_e32 v1, 0x3fb8aa3b, v1
	v_exp_f32_e32 v49, v1
	v_sub_f32_e32 v1, v51, v120
	v_mul_f32_e32 v1, 0x3fb8aa3b, v1
	v_exp_f32_e32 v52, v1
	v_sub_f32_e32 v1, v50, v120
	v_mul_f32_e32 v1, 0x3fb8aa3b, v1
	v_exp_f32_e32 v53, v1
	v_sub_f32_e32 v1, v55, v120
	v_mul_f32_e32 v1, 0x3fb8aa3b, v1
	v_exp_f32_e32 v58, v1
	v_sub_f32_e32 v1, v54, v120
	v_sub_f32_e32 v0, v26, v120
	v_mul_f32_e32 v1, 0x3fb8aa3b, v1
	v_mul_f32_e32 v0, 0x3fb8aa3b, v0
	v_exp_f32_e32 v59, v1
	v_sub_f32_e32 v1, v61, v120
	v_exp_f32_e32 v46, v0
	v_mul_f32_e32 v1, 0x3fb8aa3b, v1
	v_exp_f32_e32 v50, v1
	v_sub_f32_e32 v1, v60, v120
	v_mul_f32_e32 v1, 0x3fb8aa3b, v1
	v_exp_f32_e32 v51, v1
	v_sub_f32_e32 v1, v63, v120
	v_add_f32_e32 v0, 0, v46
	v_mul_f32_e32 v1, 0x3fb8aa3b, v1
	v_add_f32_e32 v0, v47, v0
	v_exp_f32_e32 v54, v1
	v_sub_f32_e32 v1, v62, v120
	v_add_f32_e32 v0, v56, v0
	v_mul_f32_e32 v1, 0x3fb8aa3b, v1
	v_add_f32_e32 v0, v57, v0
	v_exp_f32_e32 v55, v1
	v_sub_f32_e32 v1, v88, v120
	v_add_f32_e32 v0, v66, v0
	v_mul_f32_e32 v1, 0x3fb8aa3b, v1
	v_add_f32_e32 v0, v67, v0
	v_exp_f32_e32 v60, v1
	v_sub_f32_e32 v1, v87, v120
	v_add_f32_e32 v0, v70, v0
	v_mul_f32_e32 v1, 0x3fb8aa3b, v1
	v_add_f32_e32 v0, v71, v0
	v_exp_f32_e32 v61, v1
	v_sub_f32_e32 v1, v90, v120
	v_add_f32_e32 v0, v64, v0
	v_mul_f32_e32 v1, 0x3fb8aa3b, v1
	v_add_f32_e32 v0, v65, v0
	v_exp_f32_e32 v62, v1
	v_sub_f32_e32 v1, v89, v120
	v_add_f32_e32 v0, v68, v0
	v_mul_f32_e32 v1, 0x3fb8aa3b, v1
	v_add_f32_e32 v0, v69, v0
	v_exp_f32_e32 v63, v1
	v_sub_f32_e32 v1, v92, v120
	v_add_f32_e32 v0, v72, v0
	v_mul_f32_e32 v1, 0x3fb8aa3b, v1
	v_add_f32_e32 v0, v73, v0
	v_exp_f32_e32 v26, v1
	v_sub_f32_e32 v1, v91, v120
	v_add_f32_e32 v0, v74, v0
	v_mul_f32_e32 v1, 0x3fb8aa3b, v1
	v_add_f32_e32 v0, v75, v0
	v_exp_f32_e32 v27, v1
	v_sub_f32_e32 v1, v94, v120
	v_add_f32_e32 v0, v44, v0
	v_mul_f32_e32 v1, 0x3fb8aa3b, v1
	v_add_f32_e32 v0, v45, v0
	v_exp_f32_e32 v28, v1
	v_sub_f32_e32 v1, v93, v120
	v_add_f32_e32 v0, v48, v0
	v_mul_f32_e32 v1, 0x3fb8aa3b, v1
	v_add_f32_e32 v0, v49, v0
	v_exp_f32_e32 v29, v1
	v_sub_f32_e32 v1, v96, v120
	v_add_f32_e32 v0, v52, v0
	v_mul_f32_e32 v1, 0x3fb8aa3b, v1
	v_add_f32_e32 v0, v53, v0
	v_exp_f32_e32 v34, v1
	v_sub_f32_e32 v1, v95, v120
	v_add_f32_e32 v0, v58, v0
	v_mul_f32_e32 v1, 0x3fb8aa3b, v1
	v_add_f32_e32 v0, v59, v0
	v_exp_f32_e32 v35, v1
	v_sub_f32_e32 v1, v98, v120
	v_add_f32_e32 v0, v50, v0
	v_mul_f32_e32 v1, 0x3fb8aa3b, v1
	v_add_f32_e32 v0, v51, v0
	v_exp_f32_e32 v38, v1
	v_sub_f32_e32 v1, v97, v120
	v_add_f32_e32 v0, v54, v0
	v_mul_f32_e32 v1, 0x3fb8aa3b, v1
	v_add_f32_e32 v0, v55, v0
	v_exp_f32_e32 v39, v1
	v_sub_f32_e32 v1, v100, v120
	v_add_f32_e32 v0, v60, v0
	v_mul_f32_e32 v1, 0x3fb8aa3b, v1
	v_add_f32_e32 v0, v61, v0
	v_exp_f32_e32 v32, v1
	v_sub_f32_e32 v1, v99, v120
	v_add_f32_e32 v0, v62, v0
	v_mul_f32_e32 v1, 0x3fb8aa3b, v1
	v_add_f32_e32 v0, v63, v0
	v_exp_f32_e32 v33, v1
	v_sub_f32_e32 v1, v102, v120
	v_add_f32_e32 v0, v26, v0
	v_mul_f32_e32 v1, 0x3fb8aa3b, v1
	v_add_f32_e32 v0, v27, v0
	v_exp_f32_e32 v36, v1
	v_sub_f32_e32 v1, v101, v120
	v_add_f32_e32 v0, v28, v0
	v_mul_f32_e32 v1, 0x3fb8aa3b, v1
	v_add_f32_e32 v0, v29, v0
	v_exp_f32_e32 v37, v1
	v_sub_f32_e32 v1, v104, v120
	v_add_f32_e32 v0, v34, v0
	v_mul_f32_e32 v1, 0x3fb8aa3b, v1
	v_add_f32_e32 v0, v35, v0
	v_exp_f32_e32 v40, v1
	v_sub_f32_e32 v1, v103, v120
	v_add_f32_e32 v0, v38, v0
	v_mul_f32_e32 v1, 0x3fb8aa3b, v1
	v_add_f32_e32 v0, v39, v0
	v_exp_f32_e32 v41, v1
	v_sub_f32_e32 v1, v106, v120
	v_add_f32_e32 v0, v32, v0
	v_mul_f32_e32 v1, 0x3fb8aa3b, v1
	v_add_f32_e32 v0, v33, v0
	v_exp_f32_e32 v42, v1
	v_sub_f32_e32 v1, v105, v120
	v_add_f32_e32 v0, v36, v0
	v_mul_f32_e32 v1, 0x3fb8aa3b, v1
	v_add_f32_e32 v0, v37, v0
	v_exp_f32_e32 v43, v1
	v_add_f32_e32 v0, v40, v0
	v_add_f32_e32 v0, v41, v0
	v_add_f32_e32 v0, v42, v0
	v_add_f32_e32 v1, v43, v0
	v_sub_f32_e32 v0, v108, v120
	v_mul_f32_e32 v0, 0x3fb8aa3b, v0
	v_exp_f32_e32 v0, v0
	v_sub_f32_e32 v5, v112, v120
	v_mul_f32_e32 v5, 0x3fb8aa3b, v5
	v_exp_f32_e32 v6, v5
	v_add_f32_e32 v2, v0, v1
	v_sub_f32_e32 v1, v107, v120
	v_mul_f32_e32 v1, 0x3fb8aa3b, v1
	v_exp_f32_e32 v1, v1
	v_sub_f32_e32 v5, v111, v120
	v_mul_f32_e32 v5, 0x3fb8aa3b, v5
	v_exp_f32_e32 v7, v5
	v_add_f32_e32 v3, v1, v2
	v_sub_f32_e32 v2, v110, v120
	v_mul_f32_e32 v2, 0x3fb8aa3b, v2
	v_exp_f32_e32 v2, v2
	v_sub_f32_e32 v5, v114, v120
	v_mul_f32_e32 v5, 0x3fb8aa3b, v5
	v_exp_f32_e32 v10, v5
	v_add_f32_e32 v4, v2, v3
	v_sub_f32_e32 v3, v109, v120
	v_mul_f32_e32 v3, 0x3fb8aa3b, v3
	v_exp_f32_e32 v3, v3
	v_sub_f32_e32 v5, v113, v120
	v_mul_f32_e32 v5, 0x3fb8aa3b, v5
	v_exp_f32_e32 v11, v5
	v_add_f32_e32 v4, v3, v4
	v_add_f32_e32 v4, v6, v4
	v_add_f32_e32 v4, v7, v4
	v_add_f32_e32 v4, v10, v4
	v_add_f32_e32 v5, v11, v4
	v_sub_f32_e32 v4, v116, v120
	v_mul_f32_e32 v4, 0x3fb8aa3b, v4
	v_exp_f32_e32 v4, v4
	v_sub_f32_e32 v8, v8, v120
	v_mul_f32_e32 v8, 0x3fb8aa3b, v8
	v_sub_f32_e32 v9, v9, v120
	v_add_f32_e32 v23, v4, v5
	v_sub_f32_e32 v5, v115, v120
	v_mul_f32_e32 v5, 0x3fb8aa3b, v5
	v_exp_f32_e32 v5, v5
	v_exp_f32_e32 v8, v8
	v_mul_f32_e32 v9, 0x3fb8aa3b, v9
	v_sub_f32_e32 v22, v22, v120
	v_exp_f32_e32 v9, v9
	v_mul_f32_e32 v22, 0x3fb8aa3b, v22
	v_exp_f32_e32 v22, v22
	v_add_f32_e32 v23, v5, v23
	v_add_f32_e32 v23, v8, v23
	v_add_f32_e32 v23, v9, v23
	v_add_f32_e32 v24, v22, v23
	v_sub_f32_e32 v23, v117, v120
	v_mul_f32_e32 v23, 0x3fb8aa3b, v23
	v_exp_f32_e32 v23, v23
	s_nop 0
	v_add_f32_e32 v25, v23, v24
	v_sub_f32_e32 v24, v119, v120
	v_mul_f32_e32 v24, 0x3fb8aa3b, v24
	v_exp_f32_e32 v24, v24
	s_nop 0
	v_add_f32_e32 v30, v24, v25
	v_sub_f32_e32 v25, v118, v120
	v_mul_f32_e32 v25, 0x3fb8aa3b, v25
	v_exp_f32_e32 v25, v25
	s_nop 0
	v_add_f32_e32 v30, v25, v30
	ds_bpermute_b32 v87, v76, v30
	s_waitcnt lgkmcnt(0)
	v_add_f32_e32 v30, v30, v87
	ds_bpermute_b32 v87, v77, v30
	s_waitcnt lgkmcnt(0)
	v_add_f32_e32 v30, v30, v87
	v_rcp_f32_e32 v30, v30
	v_lshl_add_u32 v87, v86, 1, v78
	ds_read_b128 v[92:95], v87 offset:65280
	v_add_u32_e32 v86, 0xff00, v87
	v_pk_mul_f32 v[56:57], v[56:57], v[30:31] op_sel_hi:[1,0]
	v_pk_mul_f32 v[46:47], v[46:47], v[30:31] op_sel_hi:[1,0]
	v_cvt_pk_bf16_f32 v89, v56, v57
	v_pk_mul_f32 v[56:57], v[70:71], v[30:31] op_sel_hi:[1,0]
	ds_read_b128 v[96:99], v86 offset:15616
	v_cvt_pk_bf16_f32 v91, v56, v57
	v_pk_mul_f32 v[56:57], v[68:69], v[30:31] op_sel_hi:[1,0]
	ds_read_b128 v[68:71], v87 offset:65344
	v_cvt_pk_bf16_f32 v88, v46, v47
	v_pk_mul_f32 v[46:47], v[66:67], v[30:31] op_sel_hi:[1,0]
	ds_read_b128 v[100:103], v86 offset:31232
	v_cvt_pk_bf16_f32 v90, v46, v47
	v_pk_mul_f32 v[46:47], v[64:65], v[30:31] op_sel_hi:[1,0]
	v_cvt_pk_bf16_f32 v65, v56, v57
	v_cvt_pk_bf16_f32 v64, v46, v47
	v_pk_mul_f32 v[46:47], v[72:73], v[30:31] op_sel_hi:[1,0]
	v_pk_mul_f32 v[56:57], v[74:75], v[30:31] op_sel_hi:[1,0]
	v_cvt_pk_bf16_f32 v66, v46, v47
	v_cvt_pk_bf16_f32 v67, v56, v57
	ds_read_b128 v[72:75], v86 offset:15680
	v_pk_mul_f32 v[46:47], v[48:49], v[30:31] op_sel_hi:[1,0]
	v_pk_mul_f32 v[48:49], v[58:59], v[30:31] op_sel_hi:[1,0]
	ds_read_b128 v[56:59], v87 offset:65408
	s_waitcnt lgkmcnt(5)
	v_mfma_f32_16x16x32_bf16 v[92:95], v[92:95], v[88:91], 0
	ds_read_b128 v[104:107], v86 offset:46848
	v_pk_mul_f32 v[44:45], v[44:45], v[30:31] op_sel_hi:[1,0]
	v_pk_mul_f32 v[26:27], v[26:27], v[30:31] op_sel_hi:[1,0]
	s_waitcnt lgkmcnt(5)
	v_mfma_f32_16x16x32_bf16 v[96:99], v[96:99], v[88:91], 0
	v_cvt_pk_bf16_f32 v44, v44, v45
	v_cvt_pk_bf16_f32 v45, v46, v47
	v_pk_mul_f32 v[46:47], v[52:53], v[30:31] op_sel_hi:[1,0]
	s_waitcnt lgkmcnt(4)
	v_mfma_f32_16x16x32_bf16 v[68:71], v[68:71], v[64:67], v[92:95]
	v_cvt_pk_bf16_f32 v46, v46, v47
	v_cvt_pk_bf16_f32 v47, v48, v49
	v_pk_mul_f32 v[48:49], v[50:51], v[30:31] op_sel_hi:[1,0]
	v_pk_mul_f32 v[50:51], v[54:55], v[30:31] op_sel_hi:[1,0]
	v_cvt_pk_bf16_f32 v48, v48, v49
	v_cvt_pk_bf16_f32 v49, v50, v51
	v_pk_mul_f32 v[50:51], v[60:61], v[30:31] op_sel_hi:[1,0]
	v_pk_mul_f32 v[52:53], v[62:63], v[30:31] op_sel_hi:[1,0]
	s_waitcnt lgkmcnt(2)
	v_mfma_f32_16x16x32_bf16 v[72:75], v[72:75], v[64:67], v[96:99]
	ds_read_b128 v[92:95], v86 offset:31296
	v_cvt_pk_bf16_f32 v50, v50, v51
	v_cvt_pk_bf16_f32 v51, v52, v53
	ds_read_b128 v[96:99], v86 offset:46912
	ds_read_b128 v[52:55], v87 offset:65472
	s_waitcnt lgkmcnt(4)
	v_mfma_f32_16x16x32_bf16 v[56:59], v[56:59], v[44:47], v[68:71]
	v_mul_f32_e64 v28, v28, v30
	v_mul_f32_e64 v29, v29, v30
	v_cvt_pk_bf16_f32 v26, v26, v27
	v_cvt_pk_bf16_f32 v27, v28, v29
	ds_read_b128 v[68:71], v86 offset:15744
	v_mfma_f32_16x16x32_bf16 v[100:103], v[100:103], v[88:91], 0
	v_mul_f32_e64 v28, v34, v30
	v_mul_f32_e64 v29, v35, v30
	v_pk_mul_f32 v[34:35], v[38:39], v[30:31] op_sel_hi:[1,0]
	v_cvt_pk_bf16_f32 v28, v28, v29
	s_waitcnt lgkmcnt(4)
	v_mfma_f32_16x16x32_bf16 v[88:91], v[104:107], v[88:91], 0
	v_cvt_pk_bf16_f32 v29, v34, v35
	v_pk_mul_f32 v[32:33], v[32:33], v[30:31] op_sel_hi:[1,0]
	v_pk_mul_f32 v[34:35], v[36:37], v[30:31] op_sel_hi:[1,0]
	s_waitcnt lgkmcnt(3)
	v_mfma_f32_16x16x32_bf16 v[92:95], v[92:95], v[64:67], v[100:103]
	v_cvt_pk_bf16_f32 v32, v32, v33
	v_cvt_pk_bf16_f32 v33, v34, v35
	v_pk_mul_f32 v[34:35], v[40:41], v[30:31] op_sel_hi:[1,0]
	s_waitcnt lgkmcnt(2)
	v_mfma_f32_16x16x32_bf16 v[64:67], v[96:99], v[64:67], v[88:91]
	v_mul_f32_e64 v36, v42, v30
	v_mul_f32_e64 v37, v43, v30
	ds_read_b128 v[60:63], v86 offset:31424
	v_cvt_pk_bf16_f32 v34, v34, v35
	ds_read_b128 v[88:91], v86 offset:46976
	s_waitcnt lgkmcnt(3)
	v_mfma_f32_16x16x32_bf16 v[52:55], v[52:55], v[48:51], v[56:59]
	v_cvt_pk_bf16_f32 v35, v36, v37
	ds_read_b128 v[36:39], v86 offset:320
	v_pk_mul_f32 v[0:1], v[0:1], v[30:31] op_sel_hi:[1,0]
	ds_read_b128 v[56:59], v86 offset:15808
	s_waitcnt lgkmcnt(4)
	v_mfma_f32_16x16x32_bf16 v[68:71], v[68:71], v[44:47], v[72:75]
	v_mul_f32_e64 v2, v2, v30
	v_mul_f32_e64 v3, v3, v30
	v_cvt_pk_bf16_f32 v0, v0, v1
	v_cvt_pk_bf16_f32 v1, v2, v3
	ds_read_b128 v[72:75], v86 offset:31360
	s_waitcnt lgkmcnt(0)
	v_mfma_f32_16x16x32_bf16 v[72:75], v[72:75], v[44:47], v[92:95]
	v_mul_f32_e64 v2, v6, v30
	v_mul_f32_e64 v3, v7, v30
	v_pk_mul_f32 v[6:7], v[10:11], v[30:31] op_sel_hi:[1,0]
	v_cvt_pk_bf16_f32 v2, v2, v3
	v_mfma_f32_16x16x32_bf16 v[44:47], v[88:91], v[44:47], v[64:67]
	v_cvt_pk_bf16_f32 v3, v6, v7
	v_pk_mul_f32 v[4:5], v[4:5], v[30:31] op_sel_hi:[1,0]
	v_pk_mul_f32 v[6:7], v[8:9], v[30:31] op_sel_hi:[1,0]
	ds_read_b128 v[64:67], v86 offset:47040
	v_cvt_pk_bf16_f32 v4, v4, v5
	v_cvt_pk_bf16_f32 v5, v6, v7
	v_pk_mul_f32 v[6:7], v[22:23], v[30:31] op_sel_hi:[1,0]
	v_pk_mul_f32 v[8:9], v[24:25], v[30:31] op_sel_hi:[1,0]
	v_mfma_f32_16x16x32_bf16 v[56:59], v[56:59], v[48:51], v[68:71]
	v_cvt_pk_bf16_f32 v6, v6, v7
	v_cvt_pk_bf16_f32 v7, v8, v9
	ds_read_b128 v[8:11], v86 offset:448
	v_mfma_f32_16x16x32_bf16 v[60:63], v[60:63], v[48:51], v[72:75]
	ds_read_b128 v[40:43], v86 offset:15936
	ds_read_b128 v[22:25], v86 offset:16064
	s_waitcnt lgkmcnt(3)
	v_mfma_f32_16x16x32_bf16 v[44:47], v[64:67], v[48:51], v[44:47]
	ds_read_b128 v[48:51], v86 offset:256
	s_waitcnt lgkmcnt(0)
	v_mfma_f32_16x16x32_bf16 v[48:51], v[48:51], v[26:29], v[52:55]
	s_nop 2
	ds_read_b128 v[52:55], v86 offset:15872
	s_waitcnt lgkmcnt(0)
	v_mfma_f32_16x16x32_bf16 v[52:55], v[52:55], v[26:29], v[56:59]
	s_nop 2
	ds_read_b128 v[56:59], v86 offset:31488
	s_waitcnt lgkmcnt(0)
	v_mfma_f32_16x16x32_bf16 v[56:59], v[56:59], v[26:29], v[60:63]
	s_nop 2
	ds_read_b128 v[60:63], v86 offset:47104
	v_mfma_f32_16x16x32_bf16 v[36:39], v[36:39], v[32:35], v[48:51]
	s_nop 2
	ds_read_b128 v[48:51], v86 offset:47168
	s_waitcnt lgkmcnt(1)
	v_mfma_f32_16x16x32_bf16 v[26:29], v[60:63], v[26:29], v[44:47]
	s_nop 2
	ds_read_b128 v[44:47], v86 offset:31552
	v_mfma_f32_16x16x32_bf16 v[40:43], v[40:43], v[32:35], v[52:55]
	s_waitcnt lgkmcnt(0)
	v_mfma_f32_16x16x32_bf16 v[44:47], v[44:47], v[32:35], v[56:59]
	v_mfma_f32_16x16x32_bf16 v[26:29], v[48:51], v[32:35], v[26:29]
	ds_read_b128 v[32:35], v86 offset:384
	s_waitcnt lgkmcnt(0)
	v_mfma_f32_16x16x32_bf16 v[32:35], v[32:35], v[0:3], v[36:39]
	s_nop 2
	ds_read_b128 v[36:39], v86 offset:16000
	s_waitcnt lgkmcnt(0)
	v_mfma_f32_16x16x32_bf16 v[36:39], v[36:39], v[0:3], v[40:43]
	s_nop 2
	ds_read_b128 v[40:43], v86 offset:31616
	s_waitcnt lgkmcnt(0)
	v_mfma_f32_16x16x32_bf16 v[40:43], v[40:43], v[0:3], v[44:47]
	s_nop 2
	ds_read_b128 v[44:47], v86 offset:47232
	v_mfma_f32_16x16x32_bf16 v[8:11], v[8:11], v[4:7], v[32:35]
	s_nop 2
	ds_read_b128 v[32:35], v86 offset:47296
	s_waitcnt lgkmcnt(1)
	v_mfma_f32_16x16x32_bf16 v[0:3], v[44:47], v[0:3], v[26:29]
	s_nop 2
	ds_read_b128 v[26:29], v86 offset:31680
	v_mfma_f32_16x16x32_bf16 v[22:25], v[22:25], v[4:7], v[36:39]
	s_waitcnt lgkmcnt(0)
	v_mfma_f32_16x16x32_bf16 v[26:29], v[26:29], v[4:7], v[40:43]
	v_mfma_f32_16x16x32_bf16 v[0:3], v[32:35], v[4:7], v[0:3]
	v_lshlrev_b64 v[4:5], 11, v[20:21]
	v_lshl_add_u64 v[4:5], s[86:87], 0, v[4:5]
	v_lshl_add_u64 v[4:5], v[18:19], 1, v[4:5]
	v_lshl_add_u64 v[18:19], v[4:5], 0, v[192:193]
	v_cvt_pk_bf16_f32 v4, v8, v9
	v_add_co_u32_e32 v8, vcc, s0, v18
	v_readlane_b32 s0, v253, 0
	v_cvt_pk_bf16_f32 v5, v10, v11
	v_cvt_pk_bf16_f32 v6, v22, v23
	v_cvt_pk_bf16_f32 v7, v24, v25
	v_addc_co_u32_e32 v9, vcc, 0, v19, vcc
	s_add_i32 s29, s29, s0
	s_add_i32 s28, s28, s0
	v_lshl_add_u64 v[20:21], v[18:19], 0, s[6:7]
	global_store_dwordx4 v[8:9], v[4:7], off offset:1024
	s_cmpk_lt_i32 s29, 0xa00
	s_nop 0
	v_cvt_pk_bf16_f32 v4, v26, v27
	v_cvt_pk_bf16_f32 v5, v28, v29
	v_cvt_pk_bf16_f32 v6, v0, v1
	v_cvt_pk_bf16_f32 v7, v2, v3
	global_store_dwordx4 v[20:21], v[4:7], off offset:64
	s_mov_b32 s98, 0
	s_barrier
	s_cbranch_scc0 .LBB0_659

.LBB0_513:
	s_and_b32 s9, s29, 3
	s_and_b32 s0, s7, s0
	s_lshl_b32 s17, s0, 3
	s_add_i32 s7, s17, -4
	s_min_i32 s7, s7, s18
	s_cmp_lg_u32 s0, 0
	s_cselect_b32 s16, s7, 0
	s_or_b32 s0, s17, 3
	s_min_u32 s0, s0, s18
	s_sub_i32 s7, s0, s16
	s_add_i32 s7, s7, 8
	s_movk_i32 s79, 0x88
	v_readfirstlane_b32 s10, v195
	s_nop 0
	s_lshr_b32 s11, s10, 8
	s_lshr_b32 s10, s10, 6
	s_sub_i32 s0, s7, s11
	s_cmp_eq_u32 s98, 1
	s_cbranch_scc1 .Lna_L
	s_cmp_eq_u32 s98, 2
	s_cbranch_scc1 .Lna_C
.Lna_W:
	v_and_b32_e32 v0, 7, v195
	v_bfe_u32 v1, v195, 3, 5
	v_lshlrev_b32_e32 v2, 4, v0
	v_mad_u32_u24 v163, v1, s79, v2
	s_mul_i32 s14, s11, 0x1100
	v_add_u32_e32 v163, s14, v163
	v_and_b32_e32 v3, 63, v195
	v_and_b32_e32 v4, 3, v3
	v_lshlrev_b32_e32 v4, 4, v4
	v_bfe_u32 v123, v3, 2, 2
	v_lshrrev_b32_e32 v6, 4, v3
	v_mul_u32_u24_e32 v207, 0x3d0, v6
	v_lshl_add_u32 v207, v123, 6, v207
	v_add_u32_e32 v207, v207, v4
	s_and_b32 s14, s10, 1
	s_lshl_b32 s14, s14, 4
	s_lshr_b32 s15, s10, 1
	s_lshl_b32 s15, s15, 2
	s_add_i32 s14, s14, s15
	s_mulk_i32 s14, 0x3d0
	s_add_i32 s14, s14, 0xff00
	v_add_u32_e32 v207, s14, v207
	v_lshlrev_b32_e32 v7, 2, v195
	v_add_u32_e32 v122, 0x1f300, v7
	s_waitcnt vmcnt(0)
	s_and_saveexec_b64 s[34:35], s[2:3]
	ds_write_b32 v122, v161
	s_mov_b64 exec, s[34:35]
	ds_write_b64 v163, v[124:125] offset:0
	ds_write_b64 v163, v[126:127] offset:8
	ds_write_b64 v163, v[128:129] offset:8704
	ds_write_b64 v163, v[130:131] offset:8712
	ds_write_b64 v163, v[132:133] offset:17408
	ds_write_b64 v163, v[134:135] offset:17416
	ds_write_b64 v163, v[136:137] offset:26112
	ds_write_b64 v163, v[138:139] offset:26120
	s_cmp_gt_i32 s0, 8
	s_cbranch_scc0 .Lna_kwr_done
	ds_write_b64 v163, v[140:141] offset:34816
	ds_write_b64 v163, v[142:143] offset:34824
	s_cmp_gt_i32 s0, 10
	s_cbranch_scc0 .Lna_kwr_done
	ds_write_b64 v163, v[164:165] offset:43520
	ds_write_b64 v163, v[166:167] offset:43528
	s_cmp_gt_i32 s0, 12
	s_cbranch_scc0 .Lna_kwr_done
	ds_write_b64 v163, v[168:169] offset:52224
	ds_write_b64 v163, v[170:171] offset:52232
	s_cmp_gt_i32 s0, 14
	s_cbranch_scc0 .Lna_kwr_done
	ds_write_b64 v163, v[172:173] offset:60928
	ds_write_b64 v163, v[174:175] offset:60936
.Lna_kwr_done:
	ds_write_b128 v207, v[176:179]
	ds_write_b128 v207, v[180:183] offset:31232
	ds_write_b128 v207, v[184:187] offset:256
	ds_write_b128 v207, v[188:191] offset:31488
	s_add_i32 s14, s7, -8
	s_cmp_lt_i32 s14, 1
	s_cbranch_scc1 .Lna_vwr_done
	v_cmp_gt_i32_e32 vcc, s14, v123
	s_and_saveexec_b64 s[34:35], vcc
	ds_write_b128 v207, v[208:211] offset:512
	ds_write_b128 v207, v[212:215] offset:31744
	s_mov_b64 exec, s[34:35]
	s_add_i32 s14, s7, -12
	s_cmp_lt_i32 s14, 1
	s_cbranch_scc1 .Lna_vwr_done
	v_cmp_gt_i32_e32 vcc, s14, v123
	s_and_saveexec_b64 s[34:35], vcc
	ds_write_b128 v207, v[216:219] offset:768
	ds_write_b128 v207, v[244:247] offset:32000
	s_mov_b64 exec, s[34:35]
.Lna_vwr_done:
	v_mov_b32_e32 v148, v248
	v_mov_b32_e32 v149, v249
	v_mov_b32_e32 v150, v250
	v_mov_b32_e32 v151, v251
	v_mov_b32_e32 v152, v144
	v_mov_b32_e32 v153, v145
	v_mov_b32_e32 v154, v146
	v_mov_b32_e32 v155, v147
	s_waitcnt lgkmcnt(0)
	s_barrier
	v_readlane_b32 s100, v253, 0
	s_nop 3
	s_add_i32 s101, s29, s100
	s_cmpk_lt_i32 s101, 0xa00
	s_cbranch_scc0 .Lna_C
	s_mov_b32 s29, s101
	s_mov_b32 s98, 1
	s_mov_b32 s99, 1
	s_branch .LBB0_504
.Lna_L:
	v_and_b32_e32 v0, 7, v195
	v_bfe_u32 v1, v195, 3, 5
	v_lshlrev_b32_e32 v2, 4, v0
	v_lshl_add_u32 v162, v1, 9, v2
	v_and_b32_e32 v3, 63, v195
	v_and_b32_e32 v4, 3, v3
	v_lshlrev_b32_e32 v4, 4, v4
	v_bfe_u32 v123, v3, 2, 2
	v_lshrrev_b32_e32 v6, 4, v3
	v_mul_u32_u24_e32 v206, 0x28000, v6
	v_lshl_add_u32 v206, v123, 7, v206
	v_add_u32_e32 v206, v206, v4
	v_lshlrev_b32_e32 v121, 2, v195
	s_or_b32 s14, s9, s25
	s_mulk_i32 s14, 0x744
	s_add_u32 s30, s60, s14
	s_addc_u32 s31, s61, 0
	s_and_saveexec_b64 s[34:35], s[2:3]
	global_load_dword v161, v121, s[30:31]
	s_mov_b64 exec, s[34:35]
	v_readlane_b32 s12, v254, 2
	v_readlane_b32 s13, v254, 3
	s_add_i32 s14, s16, s11
	s_lshl_b32 s14, s14, 6
	s_add_i32 s14, s14, s6
	s_add_i32 s14, s14, s8
	s_lshl_b32 s14, s14, 9
	s_lshl_b32 s15, s9, 7
	s_add_u32 s14, s14, s15
	s_add_u32 s12, s12, s14
	s_addc_u32 s13, s13, 0
	global_load_dwordx4 v[124:127], v162, s[12:13]
	s_add_u32 s12, s12, 0x10000
	s_addc_u32 s13, s13, 0
	global_load_dwordx4 v[128:131], v162, s[12:13]
	s_add_u32 s12, s12, 0x10000
	s_addc_u32 s13, s13, 0
	global_load_dwordx4 v[132:135], v162, s[12:13]
	s_add_u32 s12, s12, 0x10000
	s_addc_u32 s13, s13, 0
	global_load_dwordx4 v[136:139], v162, s[12:13]
	s_cmp_gt_i32 s0, 8
	s_cbranch_scc0 .Lna_kld_done
	s_add_u32 s12, s12, 0x10000
	s_addc_u32 s13, s13, 0
	global_load_dwordx4 v[140:143], v162, s[12:13]
	s_cmp_gt_i32 s0, 10
	s_cbranch_scc0 .Lna_kld_done
	s_add_u32 s12, s12, 0x10000
	s_addc_u32 s13, s13, 0
	global_load_dwordx4 v[164:167], v162, s[12:13]
	s_cmp_gt_i32 s0, 12
	s_cbranch_scc0 .Lna_kld_done
	s_add_u32 s12, s12, 0x10000
	s_addc_u32 s13, s13, 0
	global_load_dwordx4 v[168:171], v162, s[12:13]
	s_cmp_gt_i32 s0, 14
	s_cbranch_scc0 .Lna_kld_done
	s_add_u32 s12, s12, 0x10000
	s_addc_u32 s13, s13, 0
	global_load_dwordx4 v[172:175], v162, s[12:13]
.Lna_kld_done:
	v_readlane_b32 s22, v254, 4
	v_readlane_b32 s23, v254, 5
	s_lshl_b32 s14, s16, 6
	s_add_i32 s14, s14, s6
	s_add_i32 s14, s14, s8
	s_lshl_b32 s14, s14, 1
	s_mul_i32 s15, s9, 0xa00000
	s_add_u32 s14, s14, s15
	s_mul_i32 s15, s10, 0xa0000
	s_add_u32 s14, s14, s15
	s_add_u32 s22, s22, s14
	s_addc_u32 s23, s23, 0
	s_add_u32 s30, s22, 0x500000
	s_addc_u32 s31, s23, 0
	global_load_dwordx4 v[176:179], v206, s[22:23]
	global_load_dwordx4 v[180:183], v206, s[30:31]
	global_load_dwordx4 v[184:187], v206, s[22:23] offset:512
	global_load_dwordx4 v[188:191], v206, s[30:31] offset:512
	s_add_i32 s14, s7, -8
	s_cmp_lt_i32 s14, 1
	s_cbranch_scc1 .Lna_vld_done
	v_cmp_gt_i32_e32 vcc, s14, v123
	s_and_saveexec_b64 s[34:35], vcc
	global_load_dwordx4 v[208:211], v206, s[22:23] offset:1024
	global_load_dwordx4 v[212:215], v206, s[30:31] offset:1024
	s_mov_b64 exec, s[34:35]
	s_add_i32 s14, s7, -12
	s_cmp_lt_i32 s14, 1
	s_cbranch_scc1 .Lna_vld_done
	v_cmp_gt_i32_e32 vcc, s14, v123
	s_and_saveexec_b64 s[34:35], vcc
	global_load_dwordx4 v[216:219], v206, s[22:23] offset:1536
	global_load_dwordx4 v[244:247], v206, s[30:31] offset:1536
	s_mov_b64 exec, s[34:35]
.Lna_vld_done:
	v_add_u32_e32 v0, s17, v15
	v_lshlrev_b32_e32 v0, 6, v0
	v_lshl_or_b32 v1, s19, 4, v17
	v_add3_u32 v0, s6, v1, v0
	v_ashrrev_i32_e32 v1, 31, v0
	v_lshlrev_b64 v[0:1], 9, v[0:1]
	v_readlane_b32 s12, v254, 0
	v_readlane_b32 s13, v254, 1
	s_lshl_b32 s14, s9, 7
	s_mov_b32 s15, 0
	v_lshlrev_b32_e32 v2, 1, v14
	v_mov_b32_e32 v3, 0
	s_nop 0
	v_lshl_add_u64 v[0:1], s[12:13], 0, v[0:1]
	v_lshl_add_u64 v[0:1], v[0:1], 0, s[14:15]
	v_lshl_add_u64 v[0:1], v[0:1], 0, v[2:3]
	global_load_dwordx4 v[248:251], v[0:1], off
	global_load_dwordx4 v[144:147], v[0:1], off offset:64
	s_cmp_eq_u32 s99, 0
	s_cbranch_scc1 .Lna_L0
	s_sub_i32 s29, s29, s100
	s_mov_b32 s98, 2
	s_branch .LBB0_504
.Lna_L0:
	s_mov_b32 s98, 0
	s_branch .LBB0_504

.LBB0_531:
	v_add_u32_e32 v28, s17, v15
	v_lshlrev_b32_e32 v0, 6, v28
	v_lshl_or_b32 v30, s19, 4, v17
	v_add3_u32 v20, s6, v30, v0
	v_ashrrev_i32_e32 v21, 31, v20
	v_readlane_b32 s6, v254, 0
	v_lshlrev_b64 v[0:1], 9, v[20:21]
	v_readlane_b32 s7, v254, 1
	v_lshlrev_b32_e32 v192, 1, v14
	s_nop 0
	v_lshl_add_u64 v[0:1], s[6:7], 0, v[0:1]
	v_lshl_add_u64 v[0:1], v[18:19], 1, v[0:1]
	v_lshl_add_u64 v[0:1], v[0:1], 0, v[192:193]
	v_mov_b32_e32 v156, 0xf149f2ca
	v_add_u32_e32 v8, -4, v28
	v_min_i32_e32 v8, s18, v8
	v_cmp_lt_i32_e32 vcc, 3, v28
	v_add_u32_e32 v32, s8, v14
	v_med3_i32 v35, v30, 8, 56
	v_cndmask_b32_e32 v29, 0, v8, vcc
	v_subrev_u32_e32 v8, s16, v29
	v_lshlrev_b32_e32 v86, 5, v8
	v_or_b32_e32 v8, v86, v31
	v_mad_u64_u32 v[22:23], s[6:7], v8, s79, v[16:17]
	ds_read2_b64 v[8:11], v22 offset1:1
	ds_read2_b64 v[24:27], v22 offset0:8 offset1:9
	v_sub_u32_e32 v23, v32, v35
	v_add_u32_e32 v23, 8, v23
	v_sub_u32_e32 v28, v29, v28
	s_movk_i32 s0, 0x7c
	v_cmp_gt_u32_e32 vcc, 16, v23
	v_mul_lo_u32 v23, v28, s0
	v_add_u32_e32 v33, 0x1f300, v23
	v_sub_u32_e32 v23, v32, v30
	v_med3_i32 v44, v23, -15, 15
	v_mov_b32_e32 v4, v148
	v_mov_b32_e32 v5, v149
	v_mov_b32_e32 v6, v150
	v_mov_b32_e32 v7, v151
	v_mov_b32_e32 v0, v152
	v_mov_b32_e32 v1, v153
	v_mov_b32_e32 v2, v154
	v_mov_b32_e32 v3, v155
	s_waitcnt lgkmcnt(1)
	v_mfma_f32_16x16x32_bf16 v[8:11], v[8:11], v[4:7], 0
	s_waitcnt lgkmcnt(0)
	v_mfma_f32_16x16x32_bf16 v[8:11], v[24:27], v[0:3], v[8:11]
	v_mov_b32_e32 v24, 0xf149f2ca
	v_mov_b32_e32 v26, 0xf149f2ca
	s_and_saveexec_b64 s[6:7], vcc
	s_cbranch_execz .LBB0_533
	v_lshl_add_u32 v23, v44, 2, v33
	ds_read_b32 v23, v23 offset:928
	s_waitcnt lgkmcnt(0)
	s_nop 0
	v_add_f32_e32 v26, v8, v23
